# GEMM main loop: the two B-operand LDS-DMA loads of load segments 2 and 4 are issued between the MFMAs of the following MFMA segment (4 DMA left per heavy segment, waits vmcnt 6)
# baseline (speedup 1.0000x reference)
; #define PG8_STAGE(bufoff, gbase, voff) do { _Pragma("unroll") for (int _i = 0; _i < 2; ++_i) \
;         __builtin_amdgcn_global_load_lds((const unsigned*)((const char*)(gbase) + (voff)[_i]), (LAS unsigned*)(lds + (bufoff) + ldsw + _i * 8192), 16, 0, 0); } while (0)
; #define PG8_LDA(dst, b, h) do { _Pragma("unroll") for (int m = 0; m < 4; ++m) _Pragma("unroll") for (int k = 0; k < 2; ++k) dst[m][k] = *(const LAS bf16x8*)(lds + PG8_SA(b, h) + aoff + m * 2048 + k * 1024); } while (0)
; #define PG8_LDB(dst, b, h) do { _Pragma("unroll") for (int n = 0; n < 2; ++n) _Pragma("unroll") for (int k = 0; k < 2; ++k) dst[n][k] = *(const LAS bf16x8*)(lds + PG8_SB(b, h) + boff + n * 2048 + k * 1024); } while (0)
; #define PG8_MMA(ai, bj, At, Bt) do { __builtin_amdgcn_s_setprio(1); _Pragma("unroll") for (int m = 0; m < 4; ++m) _Pragma("unroll") for (int n = 0; n < 2; ++n) _Pragma("unroll") for (int k = 0; k < 2; ++k) \
;         acc[ai][bj][m][n] = __builtin_amdgcn_mfma_f32_16x16x32_bf16(Bt[n][k], At[m][k], acc[ai][bj][m][n], 0, 0, 0); __builtin_amdgcn_s_setprio(0); } while (0)
; #define PG8_WAIT_V(n) asm volatile("s_waitcnt vmcnt(" #n ")" ::: "memory")
; #define PG8_WAIT_L(n) asm volatile("s_waitcnt lgkmcnt(" #n ")" ::: "memory")
; #define PG8_BAR __builtin_amdgcn_s_barrier()
; #define PG8_SCHED __builtin_amdgcn_sched_barrier(0)
; template <class EpiT>
; __device__ __forceinline__ void gemm_phase(LAS unsigned char* lds, const Gemm g, const StaticOrder& S, const EpiT& E, int wv) {
;     ...
;         for (int t = 0; t < nt; t += 2) {
;             const bool last = (t == nt - 2);
;             const char* a1 = cA + (size_t)(t + 1) * kstep;
;             const char* a2 = last ? nA : cA + (size_t)(t + 2) * kstep; const char* b2 = last ? nB : cB + (size_t)(t + 2) * kstep;
;             const char* a3 = a2 + kstep; const char* b3 = b2 + kstep;
;             PG8_LDB(B0, 0, 0); PG8_LDB(B1, 0, 1); PG8_SCHED; PG8_LDA(At, 0, 0); PG8_STAGE(PG8_SA(1, 1), a1 + hA, voffA);
;             PG8_WAIT_V(8); PG8_WAIT_L(0); PG8_BAR; PG8_MMA(0, 0, At, B0); PG8_MMA(0, 1, At, B1); PG8_BAR; PG8_SCHED;
;             PG8_LDA(At, 0, 1); PG8_STAGE(PG8_SB(0, 0), b2, voffB); PG8_STAGE(PG8_SB(0, 1), b2 + hB, voffB); PG8_STAGE(PG8_SA(0, 0), a2, voffA);
;             PG8_WAIT_V(8); PG8_WAIT_L(0); PG8_BAR; PG8_MMA(1, 0, At, B0); PG8_MMA(1, 1, At, B1); PG8_BAR; PG8_SCHED;
.LBB0_271:
	s_add_i32 s42, s22, 2
	s_add_u32 s43, s0, 0x80
	s_addc_u32 s23, s1, 0
	s_add_i32 s64, 0, 0x10000
	s_cmp_eq_u32 s52, s22
	s_cselect_b32 s23, s19, s23
	s_cselect_b32 s22, s18, s43
	v_add_u32_e32 v0, s64, v234
	s_cselect_b32 s45, s21, s41
	s_cselect_b32 s44, s20, s40
	s_add_i32 s43, 0, 0x14000
	ds_read_b128 v[134:137], v0
	ds_read_b128 v[138:141], v0 offset:1024
	ds_read_b128 v[142:145], v0 offset:2048
	ds_read_b128 v[146:149], v0 offset:3072
	v_add_u32_e32 v0, s43, v234
	ds_read_b128 v[150:153], v0
	ds_read_b128 v[154:157], v0 offset:1024
	ds_read_b128 v[158:161], v0 offset:2048
	ds_read_b128 v[162:165], v0 offset:3072
	s_add_i32 m0, s14, 0xc000
	ds_read_b128 v[166:169], v242
	ds_read_b128 v[170:173], v242 offset:1024
	ds_read_b128 v[174:177], v242 offset:2048
	ds_read_b128 v[178:181], v242 offset:3072
	ds_read_b128 v[204:207], v242 offset:4096
	ds_read_b128 v[208:211], v242 offset:5120
	ds_read_b128 v[212:215], v242 offset:6144
	ds_read_b128 v[216:219], v242 offset:7168
	global_load_lds_dwordx4 v196, s[0:1]
	s_add_i32 m0, s14, 0xe000
	s_nop 0
	global_load_lds_dwordx4 v198, s[0:1]
	s_waitcnt vmcnt(8)
	s_waitcnt lgkmcnt(0)
	s_barrier
	s_setprio 1
	s_waitcnt lgkmcnt(0)
	v_mfma_f32_16x16x32_bf16 v[130:133], v[134:137], v[166:169], v[130:133]
	v_mfma_f32_16x16x32_bf16 v[126:129], v[142:145], v[166:169], v[126:129]
	v_mfma_f32_16x16x32_bf16 v[114:117], v[134:137], v[174:177], v[114:117]
	v_mfma_f32_16x16x32_bf16 v[110:113], v[142:145], v[174:177], v[110:113]
	v_mfma_f32_16x16x32_bf16 v[98:101], v[134:137], v[204:207], v[98:101]
	v_mfma_f32_16x16x32_bf16 v[94:97], v[142:145], v[204:207], v[94:97]
	v_mfma_f32_16x16x32_bf16 v[82:85], v[134:137], v[212:215], v[82:85]
	v_mfma_f32_16x16x32_bf16 v[78:81], v[142:145], v[212:215], v[78:81]
	v_mfma_f32_16x16x32_bf16 v[130:133], v[138:141], v[170:173], v[130:133]
	v_mfma_f32_16x16x32_bf16 v[126:129], v[146:149], v[170:173], v[126:129]
	v_mfma_f32_16x16x32_bf16 v[114:117], v[138:141], v[178:181], v[114:117]
	v_mfma_f32_16x16x32_bf16 v[110:113], v[146:149], v[178:181], v[110:113]
	v_mfma_f32_16x16x32_bf16 v[98:101], v[138:141], v[208:211], v[98:101]
	v_mfma_f32_16x16x32_bf16 v[94:97], v[146:149], v[208:211], v[94:97]
	v_mfma_f32_16x16x32_bf16 v[82:85], v[138:141], v[216:219], v[82:85]
	v_mfma_f32_16x16x32_bf16 v[78:81], v[146:149], v[216:219], v[78:81]
	s_setprio 0
	s_setprio 1
	v_mfma_f32_16x16x32_bf16 v[122:125], v[150:153], v[166:169], v[122:125]
	v_mfma_f32_16x16x32_bf16 v[118:121], v[158:161], v[166:169], v[118:121]
	v_mfma_f32_16x16x32_bf16 v[106:109], v[150:153], v[174:177], v[106:109]
	v_mfma_f32_16x16x32_bf16 v[102:105], v[158:161], v[174:177], v[102:105]
	v_mfma_f32_16x16x32_bf16 v[90:93], v[150:153], v[204:207], v[90:93]
	v_mfma_f32_16x16x32_bf16 v[86:89], v[158:161], v[204:207], v[86:89]
	v_mfma_f32_16x16x32_bf16 v[74:77], v[150:153], v[212:215], v[74:77]
	v_mfma_f32_16x16x32_bf16 v[70:73], v[158:161], v[212:215], v[70:73]
	v_mfma_f32_16x16x32_bf16 v[122:125], v[154:157], v[170:173], v[122:125]
	v_mfma_f32_16x16x32_bf16 v[118:121], v[162:165], v[170:173], v[118:121]
	v_mfma_f32_16x16x32_bf16 v[106:109], v[154:157], v[178:181], v[106:109]
	v_mfma_f32_16x16x32_bf16 v[102:105], v[162:165], v[178:181], v[102:105]
	v_mfma_f32_16x16x32_bf16 v[90:93], v[154:157], v[208:211], v[90:93]
	v_mfma_f32_16x16x32_bf16 v[86:89], v[162:165], v[208:211], v[86:89]
	v_mfma_f32_16x16x32_bf16 v[74:77], v[154:157], v[216:219], v[74:77]
	v_mfma_f32_16x16x32_bf16 v[70:73], v[162:165], v[216:219], v[70:73]
	s_setprio 0
	s_barrier
	s_add_i32 s64, s64, s13
	s_mov_b32 m0, s64
	s_add_u32 s36, s44, 0x80
	s_addc_u32 s37, s45, 0
	ds_read_b128 v[166:169], v242 offset:16384
	ds_read_b128 v[170:173], v242 offset:17408
	ds_read_b128 v[174:177], v242 offset:18432
	ds_read_b128 v[178:181], v242 offset:19456
	ds_read_b128 v[204:207], v242 offset:20480
	ds_read_b128 v[208:211], v242 offset:21504
	ds_read_b128 v[212:215], v242 offset:22528
	ds_read_b128 v[216:219], v242 offset:23552
	global_load_lds_dwordx4 v182, s[44:45]
	s_add_i32 m0, s64, 0x2000
	s_add_i32 s43, s43, s13
	global_load_lds_dwordx4 v186, s[44:45]
	s_add_u32 s44, s44, s8
	s_addc_u32 s45, s45, 0
	s_mov_b32 m0, s43
	s_add_u32 s38, s44, 0x80
	s_addc_u32 s39, s45, 0
	global_load_lds_dwordx4 v182, s[44:45]
	s_add_i32 m0, s43, 0x2000
	s_add_u32 s46, s22, 0x80
	s_addc_u32 s47, s23, 0
	global_load_lds_dwordx4 v186, s[44:45]
	s_waitcnt vmcnt(6)
	s_waitcnt lgkmcnt(0)
	s_barrier
	s_setprio 1
	s_waitcnt lgkmcnt(0)
	v_mfma_f32_16x16x32_bf16 v[66:69], v[134:137], v[166:169], v[66:69]
	v_mfma_f32_16x16x32_bf16 v[62:65], v[142:145], v[166:169], v[62:65]
	v_mfma_f32_16x16x32_bf16 v[50:53], v[134:137], v[174:177], v[50:53]
	v_mfma_f32_16x16x32_bf16 v[46:49], v[142:145], v[174:177], v[46:49]
	v_mfma_f32_16x16x32_bf16 v[34:37], v[134:137], v[204:207], v[34:37]
	s_mov_b32 m0, s14
	v_mfma_f32_16x16x32_bf16 v[30:33], v[142:145], v[204:207], v[30:33]
	global_load_lds_dwordx4 v14, s[22:23]
	v_mfma_f32_16x16x32_bf16 v[18:21], v[134:137], v[212:215], v[18:21]
	v_mfma_f32_16x16x32_bf16 v[10:13], v[142:145], v[212:215], v[10:13]
	v_mfma_f32_16x16x32_bf16 v[66:69], v[138:141], v[170:173], v[66:69]
	v_mfma_f32_16x16x32_bf16 v[62:65], v[146:149], v[170:173], v[62:65]
	v_mfma_f32_16x16x32_bf16 v[50:53], v[138:141], v[178:181], v[50:53]
	v_mfma_f32_16x16x32_bf16 v[46:49], v[146:149], v[178:181], v[46:49]
	v_mfma_f32_16x16x32_bf16 v[34:37], v[138:141], v[208:211], v[34:37]
	v_mfma_f32_16x16x32_bf16 v[30:33], v[146:149], v[208:211], v[30:33]
	v_mfma_f32_16x16x32_bf16 v[18:21], v[138:141], v[216:219], v[18:21]
	v_mfma_f32_16x16x32_bf16 v[10:13], v[146:149], v[216:219], v[10:13]
	s_setprio 0
	s_setprio 1
	v_mfma_f32_16x16x32_bf16 v[58:61], v[150:153], v[166:169], v[58:61]
	v_mfma_f32_16x16x32_bf16 v[54:57], v[158:161], v[166:169], v[54:57]
	v_mfma_f32_16x16x32_bf16 v[42:45], v[150:153], v[174:177], v[42:45]
	v_mfma_f32_16x16x32_bf16 v[38:41], v[158:161], v[174:177], v[38:41]
	v_mfma_f32_16x16x32_bf16 v[26:29], v[150:153], v[204:207], v[26:29]
	s_mov_b32 m0, s15
	v_mfma_f32_16x16x32_bf16 v[22:25], v[158:161], v[204:207], v[22:25]
	global_load_lds_dwordx4 v184, s[22:23]
	v_mfma_f32_16x16x32_bf16 v[6:9], v[150:153], v[212:215], v[6:9]
	v_mfma_f32_16x16x32_bf16 v[2:5], v[158:161], v[212:215], v[2:5]
	v_mfma_f32_16x16x32_bf16 v[58:61], v[154:157], v[170:173], v[58:61]
	v_mfma_f32_16x16x32_bf16 v[54:57], v[162:165], v[170:173], v[54:57]
	v_mfma_f32_16x16x32_bf16 v[42:45], v[154:157], v[178:181], v[42:45]
	v_mfma_f32_16x16x32_bf16 v[38:41], v[162:165], v[178:181], v[38:41]
	v_mfma_f32_16x16x32_bf16 v[26:29], v[154:157], v[208:211], v[26:29]
	v_mfma_f32_16x16x32_bf16 v[22:25], v[162:165], v[208:211], v[22:25]
	v_mfma_f32_16x16x32_bf16 v[6:9], v[154:157], v[216:219], v[6:9]
	v_mfma_f32_16x16x32_bf16 v[2:5], v[162:165], v[216:219], v[2:5]
	s_setprio 0
	s_barrier
; #define PG8_STAGE(bufoff, gbase, voff) do { _Pragma("unroll") for (int _i = 0; _i < 2; ++_i) \
;         __builtin_amdgcn_global_load_lds((const unsigned*)((const char*)(gbase) + (voff)[_i]), (LAS unsigned*)(lds + (bufoff) + ldsw + _i * 8192), 16, 0, 0); } while (0)
; #define PG8_LDA(dst, b, h) do { _Pragma("unroll") for (int m = 0; m < 4; ++m) _Pragma("unroll") for (int k = 0; k < 2; ++k) dst[m][k] = *(const LAS bf16x8*)(lds + PG8_SA(b, h) + aoff + m * 2048 + k * 1024); } while (0)
; #define PG8_LDB(dst, b, h) do { _Pragma("unroll") for (int n = 0; n < 2; ++n) _Pragma("unroll") for (int k = 0; k < 2; ++k) dst[n][k] = *(const LAS bf16x8*)(lds + PG8_SB(b, h) + boff + n * 2048 + k * 1024); } while (0)
; #define PG8_MMA(ai, bj, At, Bt) do { __builtin_amdgcn_s_setprio(1); _Pragma("unroll") for (int m = 0; m < 4; ++m) _Pragma("unroll") for (int n = 0; n < 2; ++n) _Pragma("unroll") for (int k = 0; k < 2; ++k) \
;         acc[ai][bj][m][n] = __builtin_amdgcn_mfma_f32_16x16x32_bf16(Bt[n][k], At[m][k], acc[ai][bj][m][n], 0, 0, 0); __builtin_amdgcn_s_setprio(0); } while (0)
; #define PG8_WAIT_V(n) asm volatile("s_waitcnt vmcnt(" #n ")" ::: "memory")
; #define PG8_WAIT_L(n) asm volatile("s_waitcnt lgkmcnt(" #n ")" ::: "memory")
; #define PG8_BAR __builtin_amdgcn_s_barrier()
; #define PG8_SCHED __builtin_amdgcn_sched_barrier(0)
; template <class EpiT>
; __device__ __forceinline__ void gemm_phase(LAS unsigned char* lds, const Gemm g, const StaticOrder& S, const EpiT& E, int wv) {
;     ...
;             PG8_LDB(B0, 1, 0); PG8_LDB(B1, 1, 1); PG8_SCHED; PG8_LDA(At, 1, 0); PG8_STAGE(PG8_SA(0, 1), a2 + hA, voffA);
;             PG8_WAIT_V(8); PG8_WAIT_L(0); PG8_BAR; PG8_MMA(0, 0, At, B0); PG8_MMA(0, 1, At, B1); PG8_BAR; PG8_SCHED;
;             PG8_LDA(At, 1, 1); PG8_STAGE(PG8_SB(1, 0), b3, voffB); PG8_STAGE(PG8_SB(1, 1), b3 + hB, voffB); PG8_STAGE(PG8_SA(1, 0), a3, voffA);
;             PG8_WAIT_V(8); PG8_WAIT_L(0); PG8_BAR; PG8_MMA(1, 0, At, B0); PG8_MMA(1, 1, At, B1); PG8_BAR; PG8_SCHED;
;         }
	s_add_i32 s43, 0, 0x18000
	v_add_u32_e32 v0, s43, v234
	s_add_i32 s44, 0, 0x1c000
	ds_read_b128 v[134:137], v0
	ds_read_b128 v[138:141], v0 offset:1024
	ds_read_b128 v[142:145], v0 offset:2048
	ds_read_b128 v[146:149], v0 offset:3072
	v_add_u32_e32 v0, s44, v234
	ds_read_b128 v[150:153], v0
	ds_read_b128 v[154:157], v0 offset:1024
	ds_read_b128 v[158:161], v0 offset:2048
	ds_read_b128 v[162:165], v0 offset:3072
	s_add_u32 s22, s22, s4
	s_addc_u32 s23, s23, 0
	s_mov_b32 m0, s88
	ds_read_b128 v[166:169], v242 offset:32768
	ds_read_b128 v[170:173], v242 offset:33792
	ds_read_b128 v[174:177], v242 offset:34816
	ds_read_b128 v[178:181], v242 offset:35840
	ds_read_b128 v[204:207], v242 offset:36864
	ds_read_b128 v[208:211], v242 offset:37888
	ds_read_b128 v[212:215], v242 offset:38912
	ds_read_b128 v[216:219], v242 offset:39936
	global_load_lds_dwordx4 v14, s[22:23]
	s_mov_b32 m0, s89
	s_nop 0
	global_load_lds_dwordx4 v184, s[22:23]
	s_waitcnt vmcnt(8)
	s_waitcnt lgkmcnt(0)
	s_barrier
	s_setprio 1
	s_waitcnt lgkmcnt(0)
	v_mfma_f32_16x16x32_bf16 v[130:133], v[134:137], v[166:169], v[130:133]
	v_mfma_f32_16x16x32_bf16 v[126:129], v[142:145], v[166:169], v[126:129]
	v_mfma_f32_16x16x32_bf16 v[114:117], v[134:137], v[174:177], v[114:117]
	v_mfma_f32_16x16x32_bf16 v[110:113], v[142:145], v[174:177], v[110:113]
	v_mfma_f32_16x16x32_bf16 v[98:101], v[134:137], v[204:207], v[98:101]
	v_mfma_f32_16x16x32_bf16 v[94:97], v[142:145], v[204:207], v[94:97]
	v_mfma_f32_16x16x32_bf16 v[82:85], v[134:137], v[212:215], v[82:85]
	v_mfma_f32_16x16x32_bf16 v[78:81], v[142:145], v[212:215], v[78:81]
	v_mfma_f32_16x16x32_bf16 v[130:133], v[138:141], v[170:173], v[130:133]
	v_mfma_f32_16x16x32_bf16 v[126:129], v[146:149], v[170:173], v[126:129]
	v_mfma_f32_16x16x32_bf16 v[114:117], v[138:141], v[178:181], v[114:117]
	v_mfma_f32_16x16x32_bf16 v[110:113], v[146:149], v[178:181], v[110:113]
	v_mfma_f32_16x16x32_bf16 v[98:101], v[138:141], v[208:211], v[98:101]
	v_mfma_f32_16x16x32_bf16 v[94:97], v[146:149], v[208:211], v[94:97]
	v_mfma_f32_16x16x32_bf16 v[82:85], v[138:141], v[216:219], v[82:85]
	v_mfma_f32_16x16x32_bf16 v[78:81], v[146:149], v[216:219], v[78:81]
	s_setprio 0
	s_setprio 1
	v_mfma_f32_16x16x32_bf16 v[122:125], v[150:153], v[166:169], v[122:125]
	v_mfma_f32_16x16x32_bf16 v[118:121], v[158:161], v[166:169], v[118:121]
	v_mfma_f32_16x16x32_bf16 v[106:109], v[150:153], v[174:177], v[106:109]
	v_mfma_f32_16x16x32_bf16 v[102:105], v[158:161], v[174:177], v[102:105]
	v_mfma_f32_16x16x32_bf16 v[90:93], v[150:153], v[204:207], v[90:93]
	v_mfma_f32_16x16x32_bf16 v[86:89], v[158:161], v[204:207], v[86:89]
	v_mfma_f32_16x16x32_bf16 v[74:77], v[150:153], v[212:215], v[74:77]
	v_mfma_f32_16x16x32_bf16 v[70:73], v[158:161], v[212:215], v[70:73]
	v_mfma_f32_16x16x32_bf16 v[122:125], v[154:157], v[170:173], v[122:125]
	v_mfma_f32_16x16x32_bf16 v[118:121], v[162:165], v[170:173], v[118:121]
	v_mfma_f32_16x16x32_bf16 v[106:109], v[154:157], v[178:181], v[106:109]
	v_mfma_f32_16x16x32_bf16 v[102:105], v[162:165], v[178:181], v[102:105]
	v_mfma_f32_16x16x32_bf16 v[90:93], v[154:157], v[208:211], v[90:93]
	v_mfma_f32_16x16x32_bf16 v[86:89], v[162:165], v[208:211], v[86:89]
	v_mfma_f32_16x16x32_bf16 v[74:77], v[154:157], v[216:219], v[74:77]
	v_mfma_f32_16x16x32_bf16 v[70:73], v[162:165], v[216:219], v[70:73]
	s_setprio 0
	s_barrier
	s_add_i32 s22, s43, s13
	s_mov_b32 m0, s22
	ds_read_b128 v[166:169], v242 offset:49152
	ds_read_b128 v[170:173], v242 offset:50176
	ds_read_b128 v[174:177], v242 offset:51200
	ds_read_b128 v[178:181], v242 offset:52224
	ds_read_b128 v[204:207], v242 offset:53248
	ds_read_b128 v[208:211], v242 offset:54272
	ds_read_b128 v[212:215], v242 offset:55296
	ds_read_b128 v[216:219], v242 offset:56320
	global_load_lds_dwordx4 v182, s[36:37]
	s_add_i32 m0, s22, 0x2000
	s_add_i32 s22, s44, s13
	global_load_lds_dwordx4 v186, s[36:37]
	s_mov_b32 m0, s22
	s_nop 0
	global_load_lds_dwordx4 v182, s[38:39]
	s_add_i32 m0, s22, 0x2000
	s_nop 0
	global_load_lds_dwordx4 v186, s[38:39]
	s_waitcnt vmcnt(6)
	s_waitcnt lgkmcnt(0)
	s_barrier
	s_setprio 1
	s_waitcnt lgkmcnt(0)
	v_mfma_f32_16x16x32_bf16 v[66:69], v[134:137], v[166:169], v[66:69]
	v_mfma_f32_16x16x32_bf16 v[62:65], v[142:145], v[166:169], v[62:65]
	v_mfma_f32_16x16x32_bf16 v[50:53], v[134:137], v[174:177], v[50:53]
	v_mfma_f32_16x16x32_bf16 v[46:49], v[142:145], v[174:177], v[46:49]
	v_mfma_f32_16x16x32_bf16 v[34:37], v[134:137], v[204:207], v[34:37]
	s_mov_b32 m0, s72
	v_mfma_f32_16x16x32_bf16 v[30:33], v[142:145], v[204:207], v[30:33]
	global_load_lds_dwordx4 v14, s[46:47]
	v_mfma_f32_16x16x32_bf16 v[18:21], v[134:137], v[212:215], v[18:21]
	v_mfma_f32_16x16x32_bf16 v[10:13], v[142:145], v[212:215], v[10:13]
	v_mfma_f32_16x16x32_bf16 v[66:69], v[138:141], v[170:173], v[66:69]
	v_mfma_f32_16x16x32_bf16 v[62:65], v[146:149], v[170:173], v[62:65]
	v_mfma_f32_16x16x32_bf16 v[50:53], v[138:141], v[178:181], v[50:53]
	v_mfma_f32_16x16x32_bf16 v[46:49], v[146:149], v[178:181], v[46:49]
	v_mfma_f32_16x16x32_bf16 v[34:37], v[138:141], v[208:211], v[34:37]
	v_mfma_f32_16x16x32_bf16 v[30:33], v[146:149], v[208:211], v[30:33]
	v_mfma_f32_16x16x32_bf16 v[18:21], v[138:141], v[216:219], v[18:21]
	v_mfma_f32_16x16x32_bf16 v[10:13], v[146:149], v[216:219], v[10:13]
	s_setprio 0
	s_setprio 1
	v_mfma_f32_16x16x32_bf16 v[58:61], v[150:153], v[166:169], v[58:61]
	v_mfma_f32_16x16x32_bf16 v[54:57], v[158:161], v[166:169], v[54:57]
	v_mfma_f32_16x16x32_bf16 v[42:45], v[150:153], v[174:177], v[42:45]
	v_mfma_f32_16x16x32_bf16 v[38:41], v[158:161], v[174:177], v[38:41]
	v_mfma_f32_16x16x32_bf16 v[26:29], v[150:153], v[204:207], v[26:29]
	s_mov_b32 m0, s73
	v_mfma_f32_16x16x32_bf16 v[22:25], v[158:161], v[204:207], v[22:25]
	global_load_lds_dwordx4 v184, s[46:47]
	v_mfma_f32_16x16x32_bf16 v[6:9], v[150:153], v[212:215], v[6:9]
	v_mfma_f32_16x16x32_bf16 v[2:5], v[158:161], v[212:215], v[2:5]
	v_mfma_f32_16x16x32_bf16 v[58:61], v[154:157], v[170:173], v[58:61]
	v_mfma_f32_16x16x32_bf16 v[54:57], v[162:165], v[170:173], v[54:57]
	v_mfma_f32_16x16x32_bf16 v[42:45], v[154:157], v[178:181], v[42:45]
	v_mfma_f32_16x16x32_bf16 v[38:41], v[162:165], v[178:181], v[38:41]
	v_mfma_f32_16x16x32_bf16 v[26:29], v[154:157], v[208:211], v[26:29]
	v_mfma_f32_16x16x32_bf16 v[22:25], v[162:165], v[208:211], v[22:25]
	v_mfma_f32_16x16x32_bf16 v[6:9], v[154:157], v[216:219], v[6:9]
	v_mfma_f32_16x16x32_bf16 v[2:5], v[162:165], v[216:219], v[2:5]
	s_setprio 0
	s_barrier
	s_add_u32 s0, s0, 0x100
	s_addc_u32 s1, s1, 0
	s_add_u32 s40, s40, 0x100
	s_addc_u32 s41, s41, 0
	s_cmp_ge_i32 s42, s81
	s_mov_b32 s22, s42
	s_cbranch_scc0 .LBB0_271
	s_and_b64 vcc, exec, s[16:17]
	s_cbranch_vccnz .LBB0_278
